# stack: attention 4-tile unroll + per-lane row-sum partials, scan pass-1 rolling load window with SGPR row bases, nt hint on read-once P5 g_attn loads
# speedup vs baseline: 1.0079x; 1.0079x over previous
; __device__ __forceinline__ void scan_item(int b, int cgp, unsigned* AU, const bf16_t* LY, bf16_t* REC, float* sc) {
;     const int tid = threadIdx.x, wid = tid >> 6, lane = tid & 63, c = cgp * 64 + lane;
;     const unsigned r0 = (unsigned)b * SEQ + wid * 256;
;     unsigned* au0 = AU + c; unsigned* au1 = AU + (size_t)T * 512 + c; const bf16_t* ly = LY + c; bf16_t* rec = REC + c;
;     ...
;     { float hf = 0.f, hb = 0.f, slf = 0.f, slb = 0.f; unsigned fa[16], ba[16], fb[16], bb[16];
; #pragma unroll
;       for (int k = 0; k < 16; ++k) { fa[k] = au0[(r0 + k) * 512]; ba[k] = au1[(r0 + 255 - k) * 512]; }
; #pragma unroll 1
;       for (int blk = 0; blk < 16; blk += 2) {
; #pragma unroll
;           for (int k = 0; k < 16; ++k) { fb[k] = au0[(r0 + (blk + 1) * 16 + k) * 512]; bb[k] = au1[(r0 + 255 - ((blk + 1) * 16 + k)) * 512]; }
.LBB0_760:
	s_lshl_b32 s30, s42, 17
	s_and_b32 s43, s30, 0xfff00000
	s_and_b32 s30, s41, 0x1c0
	v_or_b32_e32 v136, s30, v196
	s_lshl_b32 s30, s42, 6
	s_and_b32 s30, s30, 0x1c0
	v_add_u32_e32 v64, s43, v213
	v_mov_b32_e32 v65, v153
	v_lshlrev_b32_e32 v152, 2, v136
	v_or_b32_e32 v138, s30, v196
	v_lshl_add_u64 v[0:1], v[64:65], 2, v[152:153]
	s_and_b32 s30, s42, 0x7ff8
	v_lshlrev_b32_e32 v152, 2, v138
	v_lshl_add_u64 v[88:89], s[20:21], 0, v[152:153]
	v_lshl_add_u64 v[66:67], s[12:13], 0, v[152:153]
	v_add_lshl_u32 v152, s30, v155, 17
	v_or_b32_e32 v2, 0x400, v152
	v_mov_b32_e32 v3, v153
	v_lshl_add_u64 v[142:143], v[2:3], 2, v[88:89]
	v_or_b32_e32 v2, 0x600, v152
	v_lshl_add_u64 v[144:145], v[2:3], 2, v[88:89]
	v_or_b32_e32 v2, 0x800, v152
	v_lshl_add_u64 v[146:147], v[2:3], 2, v[88:89]
	v_or_b32_e32 v2, 0xa00, v152
	v_lshl_add_u64 v[148:149], v[2:3], 2, v[88:89]
	v_or_b32_e32 v2, 0xc00, v152
	v_lshl_add_u64 v[150:151], v[2:3], 2, v[88:89]
	v_or_b32_e32 v2, 0xe00, v152
	s_waitcnt vmcnt(32)
	v_lshl_add_u64 v[172:173], v[2:3], 2, v[88:89]
	v_or_b32_e32 v2, 0x1000, v152
	v_lshl_add_u64 v[174:175], v[2:3], 2, v[88:89]
	v_or_b32_e32 v2, 0x1200, v152
	v_lshl_add_u64 v[176:177], v[2:3], 2, v[88:89]
	v_or_b32_e32 v2, 0x1400, v152
	v_lshl_add_u64 v[178:179], v[2:3], 2, v[88:89]
	v_or_b32_e32 v2, 0x1600, v152
	v_lshl_add_u64 v[180:181], v[2:3], 2, v[88:89]
	v_or_b32_e32 v2, 0x1800, v152
	v_lshl_add_u64 v[182:183], v[2:3], 2, v[88:89]
	v_or_b32_e32 v2, 0x1a00, v152
	v_lshl_add_u64 v[184:185], v[2:3], 2, v[88:89]
	v_or_b32_e32 v2, 0x1c00, v152
	v_or_b32_e32 v92, 0x1fe00, v152
	v_mov_b32_e32 v93, v153
	v_or_b32_e32 v90, 0x1fc00, v152
	v_mov_b32_e32 v91, v153
	v_or_b32_e32 v94, 0x1fa00, v152
	v_mov_b32_e32 v95, v153
	v_or_b32_e32 v100, 0x1f800, v152
	v_mov_b32_e32 v101, v153
	v_or_b32_e32 v96, 0x1f600, v152
	v_mov_b32_e32 v97, v153
	v_or_b32_e32 v102, 0x1f400, v152
	v_mov_b32_e32 v103, v153
	v_or_b32_e32 v108, 0x1f200, v152
	v_mov_b32_e32 v109, v153
	v_or_b32_e32 v104, 0x1f000, v152
	v_mov_b32_e32 v105, v153
	v_or_b32_e32 v112, 0x1ee00, v152
	v_mov_b32_e32 v113, v153
	v_or_b32_e32 v114, 0x1ec00, v152
	v_mov_b32_e32 v115, v153
	v_or_b32_e32 v118, 0x1ea00, v152
	v_mov_b32_e32 v119, v153
	v_or_b32_e32 v120, 0x1e800, v152
	v_mov_b32_e32 v121, v153
	v_or_b32_e32 v122, 0x1e600, v152
	v_mov_b32_e32 v123, v153
	v_or_b32_e32 v126, 0x1e400, v152
	v_mov_b32_e32 v127, v153
	v_lshl_add_u64 v[186:187], v[2:3], 2, v[88:89]
	v_or_b32_e32 v128, 0x1e200, v152
	v_mov_b32_e32 v129, v153
	v_or_b32_e32 v2, 0x1e00, v152
	v_or_b32_e32 v130, 0x1e000, v152
	v_mov_b32_e32 v131, v153
	v_lshl_add_u64 v[140:141], v[152:153], 2, v[88:89]
	s_waitcnt vmcnt(31)
	v_lshl_add_u64 v[68:69], v[92:93], 2, v[66:67]
	s_waitcnt vmcnt(29)
	v_lshl_add_u64 v[70:71], v[90:91], 2, v[66:67]
	s_waitcnt vmcnt(28)
	v_lshl_add_u64 v[72:73], v[94:95], 2, v[66:67]
	s_waitcnt vmcnt(24)
	v_lshl_add_u64 v[76:77], v[100:101], 2, v[66:67]
	s_waitcnt vmcnt(22)
	v_lshl_add_u64 v[80:81], v[96:97], 2, v[66:67]
	s_waitcnt vmcnt(17)
	v_lshl_add_u64 v[84:85], v[102:103], 2, v[66:67]
	v_lshl_add_u64 v[98:99], v[108:109], 2, v[66:67]
	v_lshl_add_u64 v[110:111], v[104:105], 2, v[66:67]
	v_lshl_add_u64 v[74:75], v[112:113], 2, v[66:67]
	v_lshl_add_u64 v[78:79], v[114:115], 2, v[66:67]
	v_lshl_add_u64 v[82:83], v[118:119], 2, v[66:67]
	v_lshl_add_u64 v[86:87], v[120:121], 2, v[66:67]
	v_lshl_add_u64 v[106:107], v[122:123], 2, v[66:67]
	v_lshl_add_u64 v[116:117], v[126:127], 2, v[66:67]
	v_lshl_add_u64 v[124:125], v[128:129], 2, v[66:67]
	v_lshl_add_u64 v[188:189], v[2:3], 2, v[88:89]
	v_lshl_add_u64 v[132:133], v[130:131], 2, v[66:67]
	v_lshl_add_u64 v[134:135], s[26:27], 0, v[0:1]
	v_lshlrev_b32_e32 v216, 2, v152
	v_lshl_add_u32 v216, v138, 2, v216
	v_add_u32_e32 v217, 0x7f800, v216
	s_mov_b64 s[98:99], s[20:21]
	s_mov_b64 s[100:101], s[12:13]
	global_load_dword v0, v216, s[98:99]
	global_load_dword v32, v217, s[100:101]
	global_load_dword v1, v216, s[98:99] offset:2048
	global_load_dword v33, v217, s[100:101] offset:-2048
	s_add_u32 s98, s98, 0x1000
	s_addc_u32 s99, s99, 0
	s_add_u32 s100, s100, 0xfffff000
	s_addc_u32 s101, s101, -1
	global_load_dword v2, v216, s[98:99]
	global_load_dword v34, v217, s[100:101]
	global_load_dword v3, v216, s[98:99] offset:2048
	global_load_dword v35, v217, s[100:101] offset:-2048
	s_add_u32 s98, s98, 0x1000
	s_addc_u32 s99, s99, 0
	s_add_u32 s100, s100, 0xfffff000
	s_addc_u32 s101, s101, -1
	global_load_dword v4, v216, s[98:99]
	global_load_dword v36, v217, s[100:101]
	global_load_dword v5, v216, s[98:99] offset:2048
	global_load_dword v37, v217, s[100:101] offset:-2048
	s_add_u32 s98, s98, 0x1000
	s_addc_u32 s99, s99, 0
	s_add_u32 s100, s100, 0xfffff000
	s_addc_u32 s101, s101, -1
	global_load_dword v6, v216, s[98:99]
	global_load_dword v38, v217, s[100:101]
	global_load_dword v7, v216, s[98:99] offset:2048
	global_load_dword v39, v217, s[100:101] offset:-2048
	s_add_u32 s98, s98, 0x1000
	s_addc_u32 s99, s99, 0
	s_add_u32 s100, s100, 0xfffff000
	s_addc_u32 s101, s101, -1
	global_load_dword v8, v216, s[98:99]
	global_load_dword v40, v217, s[100:101]
	global_load_dword v9, v216, s[98:99] offset:2048
	global_load_dword v41, v217, s[100:101] offset:-2048
	s_add_u32 s98, s98, 0x1000
	s_addc_u32 s99, s99, 0
	s_add_u32 s100, s100, 0xfffff000
	s_addc_u32 s101, s101, -1
	global_load_dword v10, v216, s[98:99]
	global_load_dword v42, v217, s[100:101]
	global_load_dword v11, v216, s[98:99] offset:2048
	global_load_dword v43, v217, s[100:101] offset:-2048
	s_add_u32 s98, s98, 0x1000
	s_addc_u32 s99, s99, 0
	s_add_u32 s100, s100, 0xfffff000
	s_addc_u32 s101, s101, -1
	global_load_dword v12, v216, s[98:99]
; __device__ __forceinline__ void h2f(unsigned w, float& lo, float& hi) { const __half2 h = *(const __half2*)&w; const float2 f = __half22float2(h); lo = f.x; hi = f.y; }
; __device__ __forceinline__ void scan_item(int b, int cgp, unsigned* AU, const bf16_t* LY, bf16_t* REC, float* sc) {
;     ...
;     { float hf = 0.f, hb = 0.f, slf = 0.f, slb = 0.f; unsigned fa[16], ba[16], fb[16], bb[16];
; #pragma unroll
;       for (int k = 0; k < 16; ++k) { fa[k] = au0[(r0 + k) * 512]; ba[k] = au1[(r0 + 255 - k) * 512]; }
; #pragma unroll 1
;       for (int blk = 0; blk < 16; blk += 2) {
; #pragma unroll
;           for (int k = 0; k < 16; ++k) { fb[k] = au0[(r0 + (blk + 1) * 16 + k) * 512]; bb[k] = au1[(r0 + 255 - ((blk + 1) * 16 + k)) * 512]; }
; #pragma unroll
;           for (int k = 0; k < 16; ++k) { float la, u; h2f(fa[k], la, u); hf = __builtin_amdgcn_exp2f(la) * hf + u; slf += la; h2f(ba[k], la, u); hb = __builtin_amdgcn_exp2f(la) * hb + u; slb += la; }
;           if (blk + 2 < 16) {
; #pragma unroll
;               for (int k = 0; k < 16; ++k) { fa[k] = au0[(r0 + (blk + 2) * 16 + k) * 512]; ba[k] = au1[(r0 + 255 - ((blk + 2) * 16 + k)) * 512]; } }
; #pragma unroll
;           for (int k = 0; k < 16; ++k) { float la, u; h2f(fb[k], la, u); hf = __builtin_amdgcn_exp2f(la) * hf + u; slf += la; h2f(bb[k], la, u); hb = __builtin_amdgcn_exp2f(la) * hb + u; slb += la; }
;       }
	global_load_dword v44, v217, s[100:101]
	global_load_dword v13, v216, s[98:99] offset:2048
	global_load_dword v45, v217, s[100:101] offset:-2048
	s_add_u32 s98, s98, 0x1000
	s_addc_u32 s99, s99, 0
	s_add_u32 s100, s100, 0xfffff000
	s_addc_u32 s101, s101, -1
	global_load_dword v14, v216, s[98:99]
	global_load_dword v46, v217, s[100:101]
	global_load_dword v15, v216, s[98:99] offset:2048
	global_load_dword v47, v217, s[100:101] offset:-2048
	s_add_u32 s98, s98, 0x1000
	s_addc_u32 s99, s99, 0
	s_add_u32 s100, s100, 0xfffff000
	s_addc_u32 s101, s101, -1
	global_load_dword v16, v216, s[98:99]
	global_load_dword v48, v217, s[100:101]
	global_load_dword v17, v216, s[98:99] offset:2048
	global_load_dword v49, v217, s[100:101] offset:-2048
	s_add_u32 s98, s98, 0x1000
	s_addc_u32 s99, s99, 0
	s_add_u32 s100, s100, 0xfffff000
	s_addc_u32 s101, s101, -1
	global_load_dword v18, v216, s[98:99]
	global_load_dword v50, v217, s[100:101]
	global_load_dword v19, v216, s[98:99] offset:2048
	global_load_dword v51, v217, s[100:101] offset:-2048
	s_add_u32 s98, s98, 0x1000
	s_addc_u32 s99, s99, 0
	s_add_u32 s100, s100, 0xfffff000
	s_addc_u32 s101, s101, -1
	global_load_dword v20, v216, s[98:99]
	global_load_dword v52, v217, s[100:101]
	global_load_dword v21, v216, s[98:99] offset:2048
	global_load_dword v53, v217, s[100:101] offset:-2048
	s_add_u32 s98, s98, 0x1000
	s_addc_u32 s99, s99, 0
	s_add_u32 s100, s100, 0xfffff000
	s_addc_u32 s101, s101, -1
	global_load_dword v22, v216, s[98:99]
	global_load_dword v54, v217, s[100:101]
	global_load_dword v23, v216, s[98:99] offset:2048
	global_load_dword v55, v217, s[100:101] offset:-2048
	s_add_u32 s98, s98, 0x1000
	s_addc_u32 s99, s99, 0
	s_add_u32 s100, s100, 0xfffff000
	s_addc_u32 s101, s101, -1
	global_load_dword v24, v216, s[98:99]
	global_load_dword v56, v217, s[100:101]
	global_load_dword v25, v216, s[98:99] offset:2048
	global_load_dword v57, v217, s[100:101] offset:-2048
	s_add_u32 s98, s98, 0x1000
	s_addc_u32 s99, s99, 0
	s_add_u32 s100, s100, 0xfffff000
	s_addc_u32 s101, s101, -1
	global_load_dword v26, v216, s[98:99]
	global_load_dword v58, v217, s[100:101]
	global_load_dword v27, v216, s[98:99] offset:2048
	global_load_dword v59, v217, s[100:101] offset:-2048
	s_add_u32 s98, s98, 0x1000
	s_addc_u32 s99, s99, 0
	s_add_u32 s100, s100, 0xfffff000
	s_addc_u32 s101, s101, -1
	global_load_dword v28, v216, s[98:99]
	global_load_dword v60, v217, s[100:101]
	global_load_dword v29, v216, s[98:99] offset:2048
	global_load_dword v61, v217, s[100:101] offset:-2048
	s_add_u32 s98, s98, 0x1000
	s_addc_u32 s99, s99, 0
	s_add_u32 s100, s100, 0xfffff000
	s_addc_u32 s101, s101, -1
	global_load_dword v30, v216, s[98:99]
	global_load_dword v62, v217, s[100:101]
	global_load_dword v31, v216, s[98:99] offset:2048
	global_load_dword v63, v217, s[100:101] offset:-2048
	s_add_u32 s98, s98, 0x1000
	s_addc_u32 s99, s99, 0
	s_add_u32 s100, s100, 0xfffff000
	s_addc_u32 s101, s101, -1
	v_mov_b32_e32 v192, 0
	v_mov_b32_e32 v193, 0
	v_mov_b32_e32 v194, 0
	v_mov_b32_e32 v195, 0
	s_mov_b32 s34, 0
.Lsc1_loop:
	s_waitcnt vmcnt(62)
	v_cvt_f32_f16_e32 v219, v0
	v_cvt_f32_f16_e32 v220, v32
	v_exp_f32_e32 v221, v219
	v_exp_f32_e32 v222, v220
	v_add_f32_e32 v194, v194, v219
	v_add_f32_e32 v195, v195, v220
	v_fma_mix_f32 v192, v221, v192, v0 op_sel:[0,0,1] op_sel_hi:[0,0,1]
	v_fma_mix_f32 v193, v222, v193, v32 op_sel:[0,0,1] op_sel_hi:[0,0,1]
	global_load_dword v0, v216, s[98:99]
	global_load_dword v32, v217, s[100:101]
	s_waitcnt vmcnt(62)
	v_cvt_f32_f16_e32 v219, v1
	v_cvt_f32_f16_e32 v220, v33
	v_exp_f32_e32 v221, v219
	v_exp_f32_e32 v222, v220
	v_add_f32_e32 v194, v194, v219
	v_add_f32_e32 v195, v195, v220
	v_fma_mix_f32 v192, v221, v192, v1 op_sel:[0,0,1] op_sel_hi:[0,0,1]
	v_fma_mix_f32 v193, v222, v193, v33 op_sel:[0,0,1] op_sel_hi:[0,0,1]
	global_load_dword v1, v216, s[98:99] offset:2048
	global_load_dword v33, v217, s[100:101] offset:-2048
	s_add_u32 s98, s98, 0x1000
	s_addc_u32 s99, s99, 0
	s_add_u32 s100, s100, 0xfffff000
	s_addc_u32 s101, s101, -1
	s_waitcnt vmcnt(62)
	v_cvt_f32_f16_e32 v219, v2
	v_cvt_f32_f16_e32 v220, v34
	v_exp_f32_e32 v221, v219
	v_exp_f32_e32 v222, v220
	v_add_f32_e32 v194, v194, v219
	v_add_f32_e32 v195, v195, v220
	v_fma_mix_f32 v192, v221, v192, v2 op_sel:[0,0,1] op_sel_hi:[0,0,1]
	v_fma_mix_f32 v193, v222, v193, v34 op_sel:[0,0,1] op_sel_hi:[0,0,1]
	global_load_dword v2, v216, s[98:99]
	global_load_dword v34, v217, s[100:101]
	s_waitcnt vmcnt(62)
	v_cvt_f32_f16_e32 v219, v3
	v_cvt_f32_f16_e32 v220, v35
	v_exp_f32_e32 v221, v219
	v_exp_f32_e32 v222, v220
	v_add_f32_e32 v194, v194, v219
	v_add_f32_e32 v195, v195, v220
	v_fma_mix_f32 v192, v221, v192, v3 op_sel:[0,0,1] op_sel_hi:[0,0,1]
	v_fma_mix_f32 v193, v222, v193, v35 op_sel:[0,0,1] op_sel_hi:[0,0,1]
	global_load_dword v3, v216, s[98:99] offset:2048
	global_load_dword v35, v217, s[100:101] offset:-2048
	s_add_u32 s98, s98, 0x1000
	s_addc_u32 s99, s99, 0
	s_add_u32 s100, s100, 0xfffff000
	s_addc_u32 s101, s101, -1
	s_waitcnt vmcnt(62)
	v_cvt_f32_f16_e32 v219, v4
	v_cvt_f32_f16_e32 v220, v36
	v_exp_f32_e32 v221, v219
	v_exp_f32_e32 v222, v220
	v_add_f32_e32 v194, v194, v219
	v_add_f32_e32 v195, v195, v220
	v_fma_mix_f32 v192, v221, v192, v4 op_sel:[0,0,1] op_sel_hi:[0,0,1]
	v_fma_mix_f32 v193, v222, v193, v36 op_sel:[0,0,1] op_sel_hi:[0,0,1]
	global_load_dword v4, v216, s[98:99]
	global_load_dword v36, v217, s[100:101]
	s_waitcnt vmcnt(62)
; __device__ __forceinline__ void h2f(unsigned w, float& lo, float& hi) { const __half2 h = *(const __half2*)&w; const float2 f = __half22float2(h); lo = f.x; hi = f.y; }
; __device__ __forceinline__ void scan_item(int b, int cgp, unsigned* AU, const bf16_t* LY, bf16_t* REC, float* sc) {
;     ...
;       for (int blk = 0; blk < 16; blk += 2) {
; #pragma unroll
;           for (int k = 0; k < 16; ++k) { fb[k] = au0[(r0 + (blk + 1) * 16 + k) * 512]; bb[k] = au1[(r0 + 255 - ((blk + 1) * 16 + k)) * 512]; }
; #pragma unroll
;           for (int k = 0; k < 16; ++k) { float la, u; h2f(fa[k], la, u); hf = __builtin_amdgcn_exp2f(la) * hf + u; slf += la; h2f(ba[k], la, u); hb = __builtin_amdgcn_exp2f(la) * hb + u; slb += la; }
;           if (blk + 2 < 16) {
; #pragma unroll
;               for (int k = 0; k < 16; ++k) { fa[k] = au0[(r0 + (blk + 2) * 16 + k) * 512]; ba[k] = au1[(r0 + 255 - ((blk + 2) * 16 + k)) * 512]; } }
; #pragma unroll
;           for (int k = 0; k < 16; ++k) { float la, u; h2f(fb[k], la, u); hf = __builtin_amdgcn_exp2f(la) * hf + u; slf += la; h2f(bb[k], la, u); hb = __builtin_amdgcn_exp2f(la) * hb + u; slb += la; }
;       }
	v_cvt_f32_f16_e32 v219, v5
	v_cvt_f32_f16_e32 v220, v37
	v_exp_f32_e32 v221, v219
	v_exp_f32_e32 v222, v220
	v_add_f32_e32 v194, v194, v219
	v_add_f32_e32 v195, v195, v220
	v_fma_mix_f32 v192, v221, v192, v5 op_sel:[0,0,1] op_sel_hi:[0,0,1]
	v_fma_mix_f32 v193, v222, v193, v37 op_sel:[0,0,1] op_sel_hi:[0,0,1]
	global_load_dword v5, v216, s[98:99] offset:2048
	global_load_dword v37, v217, s[100:101] offset:-2048
	s_add_u32 s98, s98, 0x1000
	s_addc_u32 s99, s99, 0
	s_add_u32 s100, s100, 0xfffff000
	s_addc_u32 s101, s101, -1
	s_waitcnt vmcnt(62)
	v_cvt_f32_f16_e32 v219, v6
	v_cvt_f32_f16_e32 v220, v38
	v_exp_f32_e32 v221, v219
	v_exp_f32_e32 v222, v220
	v_add_f32_e32 v194, v194, v219
	v_add_f32_e32 v195, v195, v220
	v_fma_mix_f32 v192, v221, v192, v6 op_sel:[0,0,1] op_sel_hi:[0,0,1]
	v_fma_mix_f32 v193, v222, v193, v38 op_sel:[0,0,1] op_sel_hi:[0,0,1]
	global_load_dword v6, v216, s[98:99]
	global_load_dword v38, v217, s[100:101]
	s_waitcnt vmcnt(62)
	v_cvt_f32_f16_e32 v219, v7
	v_cvt_f32_f16_e32 v220, v39
	v_exp_f32_e32 v221, v219
	v_exp_f32_e32 v222, v220
	v_add_f32_e32 v194, v194, v219
	v_add_f32_e32 v195, v195, v220
	v_fma_mix_f32 v192, v221, v192, v7 op_sel:[0,0,1] op_sel_hi:[0,0,1]
	v_fma_mix_f32 v193, v222, v193, v39 op_sel:[0,0,1] op_sel_hi:[0,0,1]
	global_load_dword v7, v216, s[98:99] offset:2048
	global_load_dword v39, v217, s[100:101] offset:-2048
	s_add_u32 s98, s98, 0x1000
	s_addc_u32 s99, s99, 0
	s_add_u32 s100, s100, 0xfffff000
	s_addc_u32 s101, s101, -1
	s_waitcnt vmcnt(62)
	v_cvt_f32_f16_e32 v219, v8
	v_cvt_f32_f16_e32 v220, v40
	v_exp_f32_e32 v221, v219
	v_exp_f32_e32 v222, v220
	v_add_f32_e32 v194, v194, v219
	v_add_f32_e32 v195, v195, v220
	v_fma_mix_f32 v192, v221, v192, v8 op_sel:[0,0,1] op_sel_hi:[0,0,1]
	v_fma_mix_f32 v193, v222, v193, v40 op_sel:[0,0,1] op_sel_hi:[0,0,1]
	global_load_dword v8, v216, s[98:99]
	global_load_dword v40, v217, s[100:101]
	s_waitcnt vmcnt(62)
	v_cvt_f32_f16_e32 v219, v9
	v_cvt_f32_f16_e32 v220, v41
	v_exp_f32_e32 v221, v219
	v_exp_f32_e32 v222, v220
	v_add_f32_e32 v194, v194, v219
	v_add_f32_e32 v195, v195, v220
	v_fma_mix_f32 v192, v221, v192, v9 op_sel:[0,0,1] op_sel_hi:[0,0,1]
	v_fma_mix_f32 v193, v222, v193, v41 op_sel:[0,0,1] op_sel_hi:[0,0,1]
	global_load_dword v9, v216, s[98:99] offset:2048
	global_load_dword v41, v217, s[100:101] offset:-2048
	s_add_u32 s98, s98, 0x1000
	s_addc_u32 s99, s99, 0
	s_add_u32 s100, s100, 0xfffff000
	s_addc_u32 s101, s101, -1
	s_waitcnt vmcnt(62)
	v_cvt_f32_f16_e32 v219, v10
	v_cvt_f32_f16_e32 v220, v42
	v_exp_f32_e32 v221, v219
	v_exp_f32_e32 v222, v220
	v_add_f32_e32 v194, v194, v219
	v_add_f32_e32 v195, v195, v220
	v_fma_mix_f32 v192, v221, v192, v10 op_sel:[0,0,1] op_sel_hi:[0,0,1]
	v_fma_mix_f32 v193, v222, v193, v42 op_sel:[0,0,1] op_sel_hi:[0,0,1]
	global_load_dword v10, v216, s[98:99]
	global_load_dword v42, v217, s[100:101]
	s_waitcnt vmcnt(62)
	v_cvt_f32_f16_e32 v219, v11
	v_cvt_f32_f16_e32 v220, v43
	v_exp_f32_e32 v221, v219
	v_exp_f32_e32 v222, v220
	v_add_f32_e32 v194, v194, v219
	v_add_f32_e32 v195, v195, v220
	v_fma_mix_f32 v192, v221, v192, v11 op_sel:[0,0,1] op_sel_hi:[0,0,1]
	v_fma_mix_f32 v193, v222, v193, v43 op_sel:[0,0,1] op_sel_hi:[0,0,1]
	global_load_dword v11, v216, s[98:99] offset:2048
	global_load_dword v43, v217, s[100:101] offset:-2048
	s_add_u32 s98, s98, 0x1000
	s_addc_u32 s99, s99, 0
	s_add_u32 s100, s100, 0xfffff000
	s_addc_u32 s101, s101, -1
	s_waitcnt vmcnt(62)
	v_cvt_f32_f16_e32 v219, v12
	v_cvt_f32_f16_e32 v220, v44
	v_exp_f32_e32 v221, v219
	v_exp_f32_e32 v222, v220
	v_add_f32_e32 v194, v194, v219
	v_add_f32_e32 v195, v195, v220
	v_fma_mix_f32 v192, v221, v192, v12 op_sel:[0,0,1] op_sel_hi:[0,0,1]
	v_fma_mix_f32 v193, v222, v193, v44 op_sel:[0,0,1] op_sel_hi:[0,0,1]
	global_load_dword v12, v216, s[98:99]
	global_load_dword v44, v217, s[100:101]
	s_waitcnt vmcnt(62)
	v_cvt_f32_f16_e32 v219, v13
	v_cvt_f32_f16_e32 v220, v45
	v_exp_f32_e32 v221, v219
	v_exp_f32_e32 v222, v220
	v_add_f32_e32 v194, v194, v219
	v_add_f32_e32 v195, v195, v220
	v_fma_mix_f32 v192, v221, v192, v13 op_sel:[0,0,1] op_sel_hi:[0,0,1]
	v_fma_mix_f32 v193, v222, v193, v45 op_sel:[0,0,1] op_sel_hi:[0,0,1]
	global_load_dword v13, v216, s[98:99] offset:2048
	global_load_dword v45, v217, s[100:101] offset:-2048
	s_add_u32 s98, s98, 0x1000
	s_addc_u32 s99, s99, 0
	s_add_u32 s100, s100, 0xfffff000
	s_addc_u32 s101, s101, -1
	s_waitcnt vmcnt(62)
	v_cvt_f32_f16_e32 v219, v14
	v_cvt_f32_f16_e32 v220, v46
	v_exp_f32_e32 v221, v219
	v_exp_f32_e32 v222, v220
	v_add_f32_e32 v194, v194, v219
	v_add_f32_e32 v195, v195, v220
	v_fma_mix_f32 v192, v221, v192, v14 op_sel:[0,0,1] op_sel_hi:[0,0,1]
	v_fma_mix_f32 v193, v222, v193, v46 op_sel:[0,0,1] op_sel_hi:[0,0,1]
	global_load_dword v14, v216, s[98:99]
	global_load_dword v46, v217, s[100:101]
	s_waitcnt vmcnt(62)
	v_cvt_f32_f16_e32 v219, v15
	v_cvt_f32_f16_e32 v220, v47
	v_exp_f32_e32 v221, v219
	v_exp_f32_e32 v222, v220
	v_add_f32_e32 v194, v194, v219
	v_add_f32_e32 v195, v195, v220
	v_fma_mix_f32 v192, v221, v192, v15 op_sel:[0,0,1] op_sel_hi:[0,0,1]
	v_fma_mix_f32 v193, v222, v193, v47 op_sel:[0,0,1] op_sel_hi:[0,0,1]
	global_load_dword v15, v216, s[98:99] offset:2048
	global_load_dword v47, v217, s[100:101] offset:-2048
	s_add_u32 s98, s98, 0x1000
	s_addc_u32 s99, s99, 0
	s_add_u32 s100, s100, 0xfffff000
	s_addc_u32 s101, s101, -1
	s_waitcnt vmcnt(62)
	v_cvt_f32_f16_e32 v219, v16
	v_cvt_f32_f16_e32 v220, v48
	v_exp_f32_e32 v221, v219
	v_exp_f32_e32 v222, v220
	v_add_f32_e32 v194, v194, v219
	v_add_f32_e32 v195, v195, v220
	v_fma_mix_f32 v192, v221, v192, v16 op_sel:[0,0,1] op_sel_hi:[0,0,1]
	v_fma_mix_f32 v193, v222, v193, v48 op_sel:[0,0,1] op_sel_hi:[0,0,1]
	global_load_dword v16, v216, s[98:99]
	global_load_dword v48, v217, s[100:101]
	s_waitcnt vmcnt(62)
; __device__ __forceinline__ void h2f(unsigned w, float& lo, float& hi) { const __half2 h = *(const __half2*)&w; const float2 f = __half22float2(h); lo = f.x; hi = f.y; }
; __device__ __forceinline__ void scan_item(int b, int cgp, unsigned* AU, const bf16_t* LY, bf16_t* REC, float* sc) {
;     ...
;       for (int blk = 0; blk < 16; blk += 2) {
; #pragma unroll
;           for (int k = 0; k < 16; ++k) { fb[k] = au0[(r0 + (blk + 1) * 16 + k) * 512]; bb[k] = au1[(r0 + 255 - ((blk + 1) * 16 + k)) * 512]; }
; #pragma unroll
;           for (int k = 0; k < 16; ++k) { float la, u; h2f(fa[k], la, u); hf = __builtin_amdgcn_exp2f(la) * hf + u; slf += la; h2f(ba[k], la, u); hb = __builtin_amdgcn_exp2f(la) * hb + u; slb += la; }
;           if (blk + 2 < 16) {
; #pragma unroll
;               for (int k = 0; k < 16; ++k) { fa[k] = au0[(r0 + (blk + 2) * 16 + k) * 512]; ba[k] = au1[(r0 + 255 - ((blk + 2) * 16 + k)) * 512]; } }
; #pragma unroll
;           for (int k = 0; k < 16; ++k) { float la, u; h2f(fb[k], la, u); hf = __builtin_amdgcn_exp2f(la) * hf + u; slf += la; h2f(bb[k], la, u); hb = __builtin_amdgcn_exp2f(la) * hb + u; slb += la; }
;       }
	v_cvt_f32_f16_e32 v219, v17
	v_cvt_f32_f16_e32 v220, v49
	v_exp_f32_e32 v221, v219
	v_exp_f32_e32 v222, v220
	v_add_f32_e32 v194, v194, v219
	v_add_f32_e32 v195, v195, v220
	v_fma_mix_f32 v192, v221, v192, v17 op_sel:[0,0,1] op_sel_hi:[0,0,1]
	v_fma_mix_f32 v193, v222, v193, v49 op_sel:[0,0,1] op_sel_hi:[0,0,1]
	global_load_dword v17, v216, s[98:99] offset:2048
	global_load_dword v49, v217, s[100:101] offset:-2048
	s_add_u32 s98, s98, 0x1000
	s_addc_u32 s99, s99, 0
	s_add_u32 s100, s100, 0xfffff000
	s_addc_u32 s101, s101, -1
	s_waitcnt vmcnt(62)
	v_cvt_f32_f16_e32 v219, v18
	v_cvt_f32_f16_e32 v220, v50
	v_exp_f32_e32 v221, v219
	v_exp_f32_e32 v222, v220
	v_add_f32_e32 v194, v194, v219
	v_add_f32_e32 v195, v195, v220
	v_fma_mix_f32 v192, v221, v192, v18 op_sel:[0,0,1] op_sel_hi:[0,0,1]
	v_fma_mix_f32 v193, v222, v193, v50 op_sel:[0,0,1] op_sel_hi:[0,0,1]
	global_load_dword v18, v216, s[98:99]
	global_load_dword v50, v217, s[100:101]
	s_waitcnt vmcnt(62)
	v_cvt_f32_f16_e32 v219, v19
	v_cvt_f32_f16_e32 v220, v51
	v_exp_f32_e32 v221, v219
	v_exp_f32_e32 v222, v220
	v_add_f32_e32 v194, v194, v219
	v_add_f32_e32 v195, v195, v220
	v_fma_mix_f32 v192, v221, v192, v19 op_sel:[0,0,1] op_sel_hi:[0,0,1]
	v_fma_mix_f32 v193, v222, v193, v51 op_sel:[0,0,1] op_sel_hi:[0,0,1]
	global_load_dword v19, v216, s[98:99] offset:2048
	global_load_dword v51, v217, s[100:101] offset:-2048
	s_add_u32 s98, s98, 0x1000
	s_addc_u32 s99, s99, 0
	s_add_u32 s100, s100, 0xfffff000
	s_addc_u32 s101, s101, -1
	s_waitcnt vmcnt(62)
	v_cvt_f32_f16_e32 v219, v20
	v_cvt_f32_f16_e32 v220, v52
	v_exp_f32_e32 v221, v219
	v_exp_f32_e32 v222, v220
	v_add_f32_e32 v194, v194, v219
	v_add_f32_e32 v195, v195, v220
	v_fma_mix_f32 v192, v221, v192, v20 op_sel:[0,0,1] op_sel_hi:[0,0,1]
	v_fma_mix_f32 v193, v222, v193, v52 op_sel:[0,0,1] op_sel_hi:[0,0,1]
	global_load_dword v20, v216, s[98:99]
	global_load_dword v52, v217, s[100:101]
	s_waitcnt vmcnt(62)
	v_cvt_f32_f16_e32 v219, v21
	v_cvt_f32_f16_e32 v220, v53
	v_exp_f32_e32 v221, v219
	v_exp_f32_e32 v222, v220
	v_add_f32_e32 v194, v194, v219
	v_add_f32_e32 v195, v195, v220
	v_fma_mix_f32 v192, v221, v192, v21 op_sel:[0,0,1] op_sel_hi:[0,0,1]
	v_fma_mix_f32 v193, v222, v193, v53 op_sel:[0,0,1] op_sel_hi:[0,0,1]
	global_load_dword v21, v216, s[98:99] offset:2048
	global_load_dword v53, v217, s[100:101] offset:-2048
	s_add_u32 s98, s98, 0x1000
	s_addc_u32 s99, s99, 0
	s_add_u32 s100, s100, 0xfffff000
	s_addc_u32 s101, s101, -1
	s_waitcnt vmcnt(62)
	v_cvt_f32_f16_e32 v219, v22
	v_cvt_f32_f16_e32 v220, v54
	v_exp_f32_e32 v221, v219
	v_exp_f32_e32 v222, v220
	v_add_f32_e32 v194, v194, v219
	v_add_f32_e32 v195, v195, v220
	v_fma_mix_f32 v192, v221, v192, v22 op_sel:[0,0,1] op_sel_hi:[0,0,1]
	v_fma_mix_f32 v193, v222, v193, v54 op_sel:[0,0,1] op_sel_hi:[0,0,1]
	global_load_dword v22, v216, s[98:99]
	global_load_dword v54, v217, s[100:101]
	s_waitcnt vmcnt(62)
	v_cvt_f32_f16_e32 v219, v23
	v_cvt_f32_f16_e32 v220, v55
	v_exp_f32_e32 v221, v219
	v_exp_f32_e32 v222, v220
	v_add_f32_e32 v194, v194, v219
	v_add_f32_e32 v195, v195, v220
	v_fma_mix_f32 v192, v221, v192, v23 op_sel:[0,0,1] op_sel_hi:[0,0,1]
	v_fma_mix_f32 v193, v222, v193, v55 op_sel:[0,0,1] op_sel_hi:[0,0,1]
	global_load_dword v23, v216, s[98:99] offset:2048
	global_load_dword v55, v217, s[100:101] offset:-2048
	s_add_u32 s98, s98, 0x1000
	s_addc_u32 s99, s99, 0
	s_add_u32 s100, s100, 0xfffff000
	s_addc_u32 s101, s101, -1
	s_waitcnt vmcnt(62)
	v_cvt_f32_f16_e32 v219, v24
	v_cvt_f32_f16_e32 v220, v56
	v_exp_f32_e32 v221, v219
	v_exp_f32_e32 v222, v220
	v_add_f32_e32 v194, v194, v219
	v_add_f32_e32 v195, v195, v220
	v_fma_mix_f32 v192, v221, v192, v24 op_sel:[0,0,1] op_sel_hi:[0,0,1]
	v_fma_mix_f32 v193, v222, v193, v56 op_sel:[0,0,1] op_sel_hi:[0,0,1]
	global_load_dword v24, v216, s[98:99]
	global_load_dword v56, v217, s[100:101]
	s_waitcnt vmcnt(62)
	v_cvt_f32_f16_e32 v219, v25
	v_cvt_f32_f16_e32 v220, v57
	v_exp_f32_e32 v221, v219
	v_exp_f32_e32 v222, v220
	v_add_f32_e32 v194, v194, v219
	v_add_f32_e32 v195, v195, v220
	v_fma_mix_f32 v192, v221, v192, v25 op_sel:[0,0,1] op_sel_hi:[0,0,1]
	v_fma_mix_f32 v193, v222, v193, v57 op_sel:[0,0,1] op_sel_hi:[0,0,1]
	global_load_dword v25, v216, s[98:99] offset:2048
	global_load_dword v57, v217, s[100:101] offset:-2048
	s_add_u32 s98, s98, 0x1000
	s_addc_u32 s99, s99, 0
	s_add_u32 s100, s100, 0xfffff000
	s_addc_u32 s101, s101, -1
	s_waitcnt vmcnt(62)
	v_cvt_f32_f16_e32 v219, v26
	v_cvt_f32_f16_e32 v220, v58
	v_exp_f32_e32 v221, v219
	v_exp_f32_e32 v222, v220
	v_add_f32_e32 v194, v194, v219
	v_add_f32_e32 v195, v195, v220
	v_fma_mix_f32 v192, v221, v192, v26 op_sel:[0,0,1] op_sel_hi:[0,0,1]
	v_fma_mix_f32 v193, v222, v193, v58 op_sel:[0,0,1] op_sel_hi:[0,0,1]
	global_load_dword v26, v216, s[98:99]
	global_load_dword v58, v217, s[100:101]
	s_waitcnt vmcnt(62)
	v_cvt_f32_f16_e32 v219, v27
	v_cvt_f32_f16_e32 v220, v59
	v_exp_f32_e32 v221, v219
	v_exp_f32_e32 v222, v220
	v_add_f32_e32 v194, v194, v219
	v_add_f32_e32 v195, v195, v220
	v_fma_mix_f32 v192, v221, v192, v27 op_sel:[0,0,1] op_sel_hi:[0,0,1]
	v_fma_mix_f32 v193, v222, v193, v59 op_sel:[0,0,1] op_sel_hi:[0,0,1]
	global_load_dword v27, v216, s[98:99] offset:2048
	global_load_dword v59, v217, s[100:101] offset:-2048
	s_add_u32 s98, s98, 0x1000
	s_addc_u32 s99, s99, 0
	s_add_u32 s100, s100, 0xfffff000
	s_addc_u32 s101, s101, -1
	s_waitcnt vmcnt(62)
	v_cvt_f32_f16_e32 v219, v28
	v_cvt_f32_f16_e32 v220, v60
	v_exp_f32_e32 v221, v219
	v_exp_f32_e32 v222, v220
	v_add_f32_e32 v194, v194, v219
	v_add_f32_e32 v195, v195, v220
	v_fma_mix_f32 v192, v221, v192, v28 op_sel:[0,0,1] op_sel_hi:[0,0,1]
	v_fma_mix_f32 v193, v222, v193, v60 op_sel:[0,0,1] op_sel_hi:[0,0,1]
	global_load_dword v28, v216, s[98:99]
	global_load_dword v60, v217, s[100:101]
	s_waitcnt vmcnt(62)
; __device__ __forceinline__ void h2f(unsigned w, float& lo, float& hi) { const __half2 h = *(const __half2*)&w; const float2 f = __half22float2(h); lo = f.x; hi = f.y; }
; __device__ __forceinline__ void scan_item(int b, int cgp, unsigned* AU, const bf16_t* LY, bf16_t* REC, float* sc) {
;     ...
;       for (int blk = 0; blk < 16; blk += 2) {
; #pragma unroll
;           for (int k = 0; k < 16; ++k) { fb[k] = au0[(r0 + (blk + 1) * 16 + k) * 512]; bb[k] = au1[(r0 + 255 - ((blk + 1) * 16 + k)) * 512]; }
; #pragma unroll
;           for (int k = 0; k < 16; ++k) { float la, u; h2f(fa[k], la, u); hf = __builtin_amdgcn_exp2f(la) * hf + u; slf += la; h2f(ba[k], la, u); hb = __builtin_amdgcn_exp2f(la) * hb + u; slb += la; }
;           if (blk + 2 < 16) {
; #pragma unroll
;               for (int k = 0; k < 16; ++k) { fa[k] = au0[(r0 + (blk + 2) * 16 + k) * 512]; ba[k] = au1[(r0 + 255 - ((blk + 2) * 16 + k)) * 512]; } }
; #pragma unroll
;           for (int k = 0; k < 16; ++k) { float la, u; h2f(fb[k], la, u); hf = __builtin_amdgcn_exp2f(la) * hf + u; slf += la; h2f(bb[k], la, u); hb = __builtin_amdgcn_exp2f(la) * hb + u; slb += la; }
;       }
;       sc[wid * 64 + lane] = __builtin_amdgcn_exp2f(slf); sc[1024 + wid * 64 + lane] = hf;
;       sc[(8 + wid) * 64 + lane] = __builtin_amdgcn_exp2f(slb); sc[1024 + (8 + wid) * 64 + lane] = hb; }
	v_cvt_f32_f16_e32 v219, v29
	v_cvt_f32_f16_e32 v220, v61
	v_exp_f32_e32 v221, v219
	v_exp_f32_e32 v222, v220
	v_add_f32_e32 v194, v194, v219
	v_add_f32_e32 v195, v195, v220
	v_fma_mix_f32 v192, v221, v192, v29 op_sel:[0,0,1] op_sel_hi:[0,0,1]
	v_fma_mix_f32 v193, v222, v193, v61 op_sel:[0,0,1] op_sel_hi:[0,0,1]
	global_load_dword v29, v216, s[98:99] offset:2048
	global_load_dword v61, v217, s[100:101] offset:-2048
	s_add_u32 s98, s98, 0x1000
	s_addc_u32 s99, s99, 0
	s_add_u32 s100, s100, 0xfffff000
	s_addc_u32 s101, s101, -1
	s_waitcnt vmcnt(62)
	v_cvt_f32_f16_e32 v219, v30
	v_cvt_f32_f16_e32 v220, v62
	v_exp_f32_e32 v221, v219
	v_exp_f32_e32 v222, v220
	v_add_f32_e32 v194, v194, v219
	v_add_f32_e32 v195, v195, v220
	v_fma_mix_f32 v192, v221, v192, v30 op_sel:[0,0,1] op_sel_hi:[0,0,1]
	v_fma_mix_f32 v193, v222, v193, v62 op_sel:[0,0,1] op_sel_hi:[0,0,1]
	global_load_dword v30, v216, s[98:99]
	global_load_dword v62, v217, s[100:101]
	s_waitcnt vmcnt(62)
	v_cvt_f32_f16_e32 v219, v31
	v_cvt_f32_f16_e32 v220, v63
	v_exp_f32_e32 v221, v219
	v_exp_f32_e32 v222, v220
	v_add_f32_e32 v194, v194, v219
	v_add_f32_e32 v195, v195, v220
	v_fma_mix_f32 v192, v221, v192, v31 op_sel:[0,0,1] op_sel_hi:[0,0,1]
	v_fma_mix_f32 v193, v222, v193, v63 op_sel:[0,0,1] op_sel_hi:[0,0,1]
	global_load_dword v31, v216, s[98:99] offset:2048
	global_load_dword v63, v217, s[100:101] offset:-2048
	s_add_u32 s98, s98, 0x1000
	s_addc_u32 s99, s99, 0
	s_add_u32 s100, s100, 0xfffff000
	s_addc_u32 s101, s101, -1
	s_add_i32 s34, s34, 1
	s_cmp_lt_u32 s34, 7
	s_cbranch_scc1 .Lsc1_loop
	s_waitcnt vmcnt(62)
	v_cvt_f32_f16_e32 v219, v0
	v_cvt_f32_f16_e32 v220, v32
	v_exp_f32_e32 v221, v219
	v_exp_f32_e32 v222, v220
	v_add_f32_e32 v194, v194, v219
	v_add_f32_e32 v195, v195, v220
	v_fma_mix_f32 v192, v221, v192, v0 op_sel:[0,0,1] op_sel_hi:[0,0,1]
	v_fma_mix_f32 v193, v222, v193, v32 op_sel:[0,0,1] op_sel_hi:[0,0,1]
	s_waitcnt vmcnt(60)
	v_cvt_f32_f16_e32 v219, v1
	v_cvt_f32_f16_e32 v220, v33
	v_exp_f32_e32 v221, v219
	v_exp_f32_e32 v222, v220
	v_add_f32_e32 v194, v194, v219
	v_add_f32_e32 v195, v195, v220
	v_fma_mix_f32 v192, v221, v192, v1 op_sel:[0,0,1] op_sel_hi:[0,0,1]
	v_fma_mix_f32 v193, v222, v193, v33 op_sel:[0,0,1] op_sel_hi:[0,0,1]
	s_waitcnt vmcnt(58)
	v_cvt_f32_f16_e32 v219, v2
	v_cvt_f32_f16_e32 v220, v34
	v_exp_f32_e32 v221, v219
	v_exp_f32_e32 v222, v220
	v_add_f32_e32 v194, v194, v219
	v_add_f32_e32 v195, v195, v220
	v_fma_mix_f32 v192, v221, v192, v2 op_sel:[0,0,1] op_sel_hi:[0,0,1]
	v_fma_mix_f32 v193, v222, v193, v34 op_sel:[0,0,1] op_sel_hi:[0,0,1]
	s_waitcnt vmcnt(56)
	v_cvt_f32_f16_e32 v219, v3
	v_cvt_f32_f16_e32 v220, v35
	v_exp_f32_e32 v221, v219
	v_exp_f32_e32 v222, v220
	v_add_f32_e32 v194, v194, v219
	v_add_f32_e32 v195, v195, v220
	v_fma_mix_f32 v192, v221, v192, v3 op_sel:[0,0,1] op_sel_hi:[0,0,1]
	v_fma_mix_f32 v193, v222, v193, v35 op_sel:[0,0,1] op_sel_hi:[0,0,1]
	s_waitcnt vmcnt(54)
	v_cvt_f32_f16_e32 v219, v4
	v_cvt_f32_f16_e32 v220, v36
	v_exp_f32_e32 v221, v219
	v_exp_f32_e32 v222, v220
	v_add_f32_e32 v194, v194, v219
	v_add_f32_e32 v195, v195, v220
	v_fma_mix_f32 v192, v221, v192, v4 op_sel:[0,0,1] op_sel_hi:[0,0,1]
	v_fma_mix_f32 v193, v222, v193, v36 op_sel:[0,0,1] op_sel_hi:[0,0,1]
	s_waitcnt vmcnt(52)
	v_cvt_f32_f16_e32 v219, v5
	v_cvt_f32_f16_e32 v220, v37
	v_exp_f32_e32 v221, v219
	v_exp_f32_e32 v222, v220
	v_add_f32_e32 v194, v194, v219
	v_add_f32_e32 v195, v195, v220
	v_fma_mix_f32 v192, v221, v192, v5 op_sel:[0,0,1] op_sel_hi:[0,0,1]
	v_fma_mix_f32 v193, v222, v193, v37 op_sel:[0,0,1] op_sel_hi:[0,0,1]
	s_waitcnt vmcnt(50)
	v_cvt_f32_f16_e32 v219, v6
	v_cvt_f32_f16_e32 v220, v38
	v_exp_f32_e32 v221, v219
	v_exp_f32_e32 v222, v220
	v_add_f32_e32 v194, v194, v219
	v_add_f32_e32 v195, v195, v220
	v_fma_mix_f32 v192, v221, v192, v6 op_sel:[0,0,1] op_sel_hi:[0,0,1]
	v_fma_mix_f32 v193, v222, v193, v38 op_sel:[0,0,1] op_sel_hi:[0,0,1]
	s_waitcnt vmcnt(48)
	v_cvt_f32_f16_e32 v219, v7
	v_cvt_f32_f16_e32 v220, v39
	v_exp_f32_e32 v221, v219
	v_exp_f32_e32 v222, v220
	v_add_f32_e32 v194, v194, v219
	v_add_f32_e32 v195, v195, v220
	v_fma_mix_f32 v192, v221, v192, v7 op_sel:[0,0,1] op_sel_hi:[0,0,1]
	v_fma_mix_f32 v193, v222, v193, v39 op_sel:[0,0,1] op_sel_hi:[0,0,1]
	s_waitcnt vmcnt(46)
	v_cvt_f32_f16_e32 v219, v8
	v_cvt_f32_f16_e32 v220, v40
	v_exp_f32_e32 v221, v219
	v_exp_f32_e32 v222, v220
	v_add_f32_e32 v194, v194, v219
	v_add_f32_e32 v195, v195, v220
	v_fma_mix_f32 v192, v221, v192, v8 op_sel:[0,0,1] op_sel_hi:[0,0,1]
	v_fma_mix_f32 v193, v222, v193, v40 op_sel:[0,0,1] op_sel_hi:[0,0,1]
	s_waitcnt vmcnt(44)
	v_cvt_f32_f16_e32 v219, v9
	v_cvt_f32_f16_e32 v220, v41
	v_exp_f32_e32 v221, v219
	v_exp_f32_e32 v222, v220
	v_add_f32_e32 v194, v194, v219
	v_add_f32_e32 v195, v195, v220
	v_fma_mix_f32 v192, v221, v192, v9 op_sel:[0,0,1] op_sel_hi:[0,0,1]
	v_fma_mix_f32 v193, v222, v193, v41 op_sel:[0,0,1] op_sel_hi:[0,0,1]
	s_waitcnt vmcnt(42)
	v_cvt_f32_f16_e32 v219, v10
	v_cvt_f32_f16_e32 v220, v42
	v_exp_f32_e32 v221, v219
	v_exp_f32_e32 v222, v220
	v_add_f32_e32 v194, v194, v219
	v_add_f32_e32 v195, v195, v220
	v_fma_mix_f32 v192, v221, v192, v10 op_sel:[0,0,1] op_sel_hi:[0,0,1]
	v_fma_mix_f32 v193, v222, v193, v42 op_sel:[0,0,1] op_sel_hi:[0,0,1]
	s_waitcnt vmcnt(40)
	v_cvt_f32_f16_e32 v219, v11
	v_cvt_f32_f16_e32 v220, v43
	v_exp_f32_e32 v221, v219
	v_exp_f32_e32 v222, v220
	v_add_f32_e32 v194, v194, v219
	v_add_f32_e32 v195, v195, v220
	v_fma_mix_f32 v192, v221, v192, v11 op_sel:[0,0,1] op_sel_hi:[0,0,1]
	v_fma_mix_f32 v193, v222, v193, v43 op_sel:[0,0,1] op_sel_hi:[0,0,1]
	s_waitcnt vmcnt(38)
; __device__ __forceinline__ void h2f(unsigned w, float& lo, float& hi) { const __half2 h = *(const __half2*)&w; const float2 f = __half22float2(h); lo = f.x; hi = f.y; }
; __device__ __forceinline__ void scan_item(int b, int cgp, unsigned* AU, const bf16_t* LY, bf16_t* REC, float* sc) {
;     ...
;           for (int k = 0; k < 16; ++k) { float la, u; h2f(fa[k], la, u); hf = __builtin_amdgcn_exp2f(la) * hf + u; slf += la; h2f(ba[k], la, u); hb = __builtin_amdgcn_exp2f(la) * hb + u; slb += la; }
;           if (blk + 2 < 16) {
; #pragma unroll
;               for (int k = 0; k < 16; ++k) { fa[k] = au0[(r0 + (blk + 2) * 16 + k) * 512]; ba[k] = au1[(r0 + 255 - ((blk + 2) * 16 + k)) * 512]; } }
; #pragma unroll
;           for (int k = 0; k < 16; ++k) { float la, u; h2f(fb[k], la, u); hf = __builtin_amdgcn_exp2f(la) * hf + u; slf += la; h2f(bb[k], la, u); hb = __builtin_amdgcn_exp2f(la) * hb + u; slb += la; }
;       }
;       sc[wid * 64 + lane] = __builtin_amdgcn_exp2f(slf); sc[1024 + wid * 64 + lane] = hf;
;       sc[(8 + wid) * 64 + lane] = __builtin_amdgcn_exp2f(slb); sc[1024 + (8 + wid) * 64 + lane] = hb; }
	v_cvt_f32_f16_e32 v219, v12
	v_cvt_f32_f16_e32 v220, v44
	v_exp_f32_e32 v221, v219
	v_exp_f32_e32 v222, v220
	v_add_f32_e32 v194, v194, v219
	v_add_f32_e32 v195, v195, v220
	v_fma_mix_f32 v192, v221, v192, v12 op_sel:[0,0,1] op_sel_hi:[0,0,1]
	v_fma_mix_f32 v193, v222, v193, v44 op_sel:[0,0,1] op_sel_hi:[0,0,1]
	s_waitcnt vmcnt(36)
	v_cvt_f32_f16_e32 v219, v13
	v_cvt_f32_f16_e32 v220, v45
	v_exp_f32_e32 v221, v219
	v_exp_f32_e32 v222, v220
	v_add_f32_e32 v194, v194, v219
	v_add_f32_e32 v195, v195, v220
	v_fma_mix_f32 v192, v221, v192, v13 op_sel:[0,0,1] op_sel_hi:[0,0,1]
	v_fma_mix_f32 v193, v222, v193, v45 op_sel:[0,0,1] op_sel_hi:[0,0,1]
	s_waitcnt vmcnt(34)
	v_cvt_f32_f16_e32 v219, v14
	v_cvt_f32_f16_e32 v220, v46
	v_exp_f32_e32 v221, v219
	v_exp_f32_e32 v222, v220
	v_add_f32_e32 v194, v194, v219
	v_add_f32_e32 v195, v195, v220
	v_fma_mix_f32 v192, v221, v192, v14 op_sel:[0,0,1] op_sel_hi:[0,0,1]
	v_fma_mix_f32 v193, v222, v193, v46 op_sel:[0,0,1] op_sel_hi:[0,0,1]
	s_waitcnt vmcnt(32)
	v_cvt_f32_f16_e32 v219, v15
	v_cvt_f32_f16_e32 v220, v47
	v_exp_f32_e32 v221, v219
	v_exp_f32_e32 v222, v220
	v_add_f32_e32 v194, v194, v219
	v_add_f32_e32 v195, v195, v220
	v_fma_mix_f32 v192, v221, v192, v15 op_sel:[0,0,1] op_sel_hi:[0,0,1]
	v_fma_mix_f32 v193, v222, v193, v47 op_sel:[0,0,1] op_sel_hi:[0,0,1]
	s_waitcnt vmcnt(30)
	v_cvt_f32_f16_e32 v219, v16
	v_cvt_f32_f16_e32 v220, v48
	v_exp_f32_e32 v221, v219
	v_exp_f32_e32 v222, v220
	v_add_f32_e32 v194, v194, v219
	v_add_f32_e32 v195, v195, v220
	v_fma_mix_f32 v192, v221, v192, v16 op_sel:[0,0,1] op_sel_hi:[0,0,1]
	v_fma_mix_f32 v193, v222, v193, v48 op_sel:[0,0,1] op_sel_hi:[0,0,1]
	s_waitcnt vmcnt(28)
	v_cvt_f32_f16_e32 v219, v17
	v_cvt_f32_f16_e32 v220, v49
	v_exp_f32_e32 v221, v219
	v_exp_f32_e32 v222, v220
	v_add_f32_e32 v194, v194, v219
	v_add_f32_e32 v195, v195, v220
	v_fma_mix_f32 v192, v221, v192, v17 op_sel:[0,0,1] op_sel_hi:[0,0,1]
	v_fma_mix_f32 v193, v222, v193, v49 op_sel:[0,0,1] op_sel_hi:[0,0,1]
	s_waitcnt vmcnt(26)
	v_cvt_f32_f16_e32 v219, v18
	v_cvt_f32_f16_e32 v220, v50
	v_exp_f32_e32 v221, v219
	v_exp_f32_e32 v222, v220
	v_add_f32_e32 v194, v194, v219
	v_add_f32_e32 v195, v195, v220
	v_fma_mix_f32 v192, v221, v192, v18 op_sel:[0,0,1] op_sel_hi:[0,0,1]
	v_fma_mix_f32 v193, v222, v193, v50 op_sel:[0,0,1] op_sel_hi:[0,0,1]
	s_waitcnt vmcnt(24)
	v_cvt_f32_f16_e32 v219, v19
	v_cvt_f32_f16_e32 v220, v51
	v_exp_f32_e32 v221, v219
	v_exp_f32_e32 v222, v220
	v_add_f32_e32 v194, v194, v219
	v_add_f32_e32 v195, v195, v220
	v_fma_mix_f32 v192, v221, v192, v19 op_sel:[0,0,1] op_sel_hi:[0,0,1]
	v_fma_mix_f32 v193, v222, v193, v51 op_sel:[0,0,1] op_sel_hi:[0,0,1]
	s_waitcnt vmcnt(22)
	v_cvt_f32_f16_e32 v219, v20
	v_cvt_f32_f16_e32 v220, v52
	v_exp_f32_e32 v221, v219
	v_exp_f32_e32 v222, v220
	v_add_f32_e32 v194, v194, v219
	v_add_f32_e32 v195, v195, v220
	v_fma_mix_f32 v192, v221, v192, v20 op_sel:[0,0,1] op_sel_hi:[0,0,1]
	v_fma_mix_f32 v193, v222, v193, v52 op_sel:[0,0,1] op_sel_hi:[0,0,1]
	s_waitcnt vmcnt(20)
	v_cvt_f32_f16_e32 v219, v21
	v_cvt_f32_f16_e32 v220, v53
	v_exp_f32_e32 v221, v219
	v_exp_f32_e32 v222, v220
	v_add_f32_e32 v194, v194, v219
	v_add_f32_e32 v195, v195, v220
	v_fma_mix_f32 v192, v221, v192, v21 op_sel:[0,0,1] op_sel_hi:[0,0,1]
	v_fma_mix_f32 v193, v222, v193, v53 op_sel:[0,0,1] op_sel_hi:[0,0,1]
	s_waitcnt vmcnt(18)
	v_cvt_f32_f16_e32 v219, v22
	v_cvt_f32_f16_e32 v220, v54
	v_exp_f32_e32 v221, v219
	v_exp_f32_e32 v222, v220
	v_add_f32_e32 v194, v194, v219
	v_add_f32_e32 v195, v195, v220
	v_fma_mix_f32 v192, v221, v192, v22 op_sel:[0,0,1] op_sel_hi:[0,0,1]
	v_fma_mix_f32 v193, v222, v193, v54 op_sel:[0,0,1] op_sel_hi:[0,0,1]
	s_waitcnt vmcnt(16)
	v_cvt_f32_f16_e32 v219, v23
	v_cvt_f32_f16_e32 v220, v55
	v_exp_f32_e32 v221, v219
	v_exp_f32_e32 v222, v220
	v_add_f32_e32 v194, v194, v219
	v_add_f32_e32 v195, v195, v220
	v_fma_mix_f32 v192, v221, v192, v23 op_sel:[0,0,1] op_sel_hi:[0,0,1]
	v_fma_mix_f32 v193, v222, v193, v55 op_sel:[0,0,1] op_sel_hi:[0,0,1]
	s_waitcnt vmcnt(14)
	v_cvt_f32_f16_e32 v219, v24
	v_cvt_f32_f16_e32 v220, v56
	v_exp_f32_e32 v221, v219
	v_exp_f32_e32 v222, v220
	v_add_f32_e32 v194, v194, v219
	v_add_f32_e32 v195, v195, v220
	v_fma_mix_f32 v192, v221, v192, v24 op_sel:[0,0,1] op_sel_hi:[0,0,1]
	v_fma_mix_f32 v193, v222, v193, v56 op_sel:[0,0,1] op_sel_hi:[0,0,1]
	s_waitcnt vmcnt(12)
	v_cvt_f32_f16_e32 v219, v25
	v_cvt_f32_f16_e32 v220, v57
	v_exp_f32_e32 v221, v219
	v_exp_f32_e32 v222, v220
	v_add_f32_e32 v194, v194, v219
	v_add_f32_e32 v195, v195, v220
	v_fma_mix_f32 v192, v221, v192, v25 op_sel:[0,0,1] op_sel_hi:[0,0,1]
	v_fma_mix_f32 v193, v222, v193, v57 op_sel:[0,0,1] op_sel_hi:[0,0,1]
	s_waitcnt vmcnt(10)
	v_cvt_f32_f16_e32 v219, v26
	v_cvt_f32_f16_e32 v220, v58
	v_exp_f32_e32 v221, v219
	v_exp_f32_e32 v222, v220
	v_add_f32_e32 v194, v194, v219
	v_add_f32_e32 v195, v195, v220
	v_fma_mix_f32 v192, v221, v192, v26 op_sel:[0,0,1] op_sel_hi:[0,0,1]
	v_fma_mix_f32 v193, v222, v193, v58 op_sel:[0,0,1] op_sel_hi:[0,0,1]
	s_waitcnt vmcnt(8)
	v_cvt_f32_f16_e32 v219, v27
	v_cvt_f32_f16_e32 v220, v59
	v_exp_f32_e32 v221, v219
	v_exp_f32_e32 v222, v220
	v_add_f32_e32 v194, v194, v219
	v_add_f32_e32 v195, v195, v220
	v_fma_mix_f32 v192, v221, v192, v27 op_sel:[0,0,1] op_sel_hi:[0,0,1]
	v_fma_mix_f32 v193, v222, v193, v59 op_sel:[0,0,1] op_sel_hi:[0,0,1]
	s_waitcnt vmcnt(6)
	v_cvt_f32_f16_e32 v219, v28
	v_cvt_f32_f16_e32 v220, v60
	v_exp_f32_e32 v221, v219
	v_exp_f32_e32 v222, v220
	v_add_f32_e32 v194, v194, v219
	v_add_f32_e32 v195, v195, v220
	v_fma_mix_f32 v192, v221, v192, v28 op_sel:[0,0,1] op_sel_hi:[0,0,1]
	v_fma_mix_f32 v193, v222, v193, v60 op_sel:[0,0,1] op_sel_hi:[0,0,1]
	s_waitcnt vmcnt(4)
	v_cvt_f32_f16_e32 v219, v29
	v_cvt_f32_f16_e32 v220, v61
	v_exp_f32_e32 v221, v219
	v_exp_f32_e32 v222, v220
	v_add_f32_e32 v194, v194, v219
	v_add_f32_e32 v195, v195, v220
	v_fma_mix_f32 v192, v221, v192, v29 op_sel:[0,0,1] op_sel_hi:[0,0,1]
	v_fma_mix_f32 v193, v222, v193, v61 op_sel:[0,0,1] op_sel_hi:[0,0,1]
	s_waitcnt vmcnt(2)
	v_cvt_f32_f16_e32 v219, v30
	v_cvt_f32_f16_e32 v220, v62
	v_exp_f32_e32 v221, v219
	v_exp_f32_e32 v222, v220
	v_add_f32_e32 v194, v194, v219
	v_add_f32_e32 v195, v195, v220
	v_fma_mix_f32 v192, v221, v192, v30 op_sel:[0,0,1] op_sel_hi:[0,0,1]
	v_fma_mix_f32 v193, v222, v193, v62 op_sel:[0,0,1] op_sel_hi:[0,0,1]
	s_waitcnt vmcnt(0)
	v_cvt_f32_f16_e32 v219, v31
	v_cvt_f32_f16_e32 v220, v63
	v_exp_f32_e32 v221, v219
	v_exp_f32_e32 v222, v220
	v_add_f32_e32 v194, v194, v219
	v_add_f32_e32 v195, v195, v220
	v_fma_mix_f32 v192, v221, v192, v31 op_sel:[0,0,1] op_sel_hi:[0,0,1]
	v_fma_mix_f32 v193, v222, v193, v63 op_sel:[0,0,1] op_sel_hi:[0,0,1]

;     __device__ __forceinline__ void operator()(Acc& acc, const Unit& u, int wr, int wc, int fr, int fq) const {
;     ...
;         for (int ai = 0; ai < 2; ++ai) {
;             u32x4 gw_[4][2], hw_[4][2];
; #pragma unroll
;             for (int m = 0; m < 4; ++m)
; #pragma unroll
;                 for (int bj = 0; bj < 2; ++bj) { const unsigned o = (unsigned)((rowt + ai * 128 + m * 16) * 2048 + c0 + bj * 128);
;                     gw_[m][bj] = *(const u32x4*)(GATES + (o + 1024)); if (u.sel == 0) hw_[m][bj] = *(const u32x4*)(GATES + o); else hw_[m][bj] = gw_[m][bj]; }
.LBB0_892:
	v_lshl_or_b32 v212, s6, 8, v221
	s_lshl_b32 s4, s4, 19
	v_add3_u32 v2, s4, v220, v212
	s_waitcnt vmcnt(0)
	s_cmp_eq_u32 s5, 0
	s_cselect_b64 s[6:7], -1, 0
	s_cmp_lg_u32 s5, 0
	s_cselect_b64 s[50:51], -1, 0
	v_cndmask_b32_e64 v0, 0, 1, s[6:7]
	v_cmp_ne_u32_e64 s[4:5], 1, v0
	v_add_u32_e32 v0, 0x400, v2
	v_lshl_add_u64 v[132:133], v[0:1], 1, s[16:17]
	global_load_dwordx4 v[192:195], v[132:133], off
	v_add_u32_e32 v0, 0x480, v2
	v_lshl_add_u64 v[132:133], v[0:1], 1, s[16:17]
	global_load_dwordx4 v[184:187], v[132:133], off
	v_add_u32_e32 v0, 0x8400, v2
	v_lshl_add_u64 v[132:133], v[0:1], 1, s[16:17]
	global_load_dwordx4 v[176:179], v[132:133], off
	v_add_u32_e32 v0, 0x8480, v2
	v_lshl_add_u64 v[132:133], v[0:1], 1, s[16:17]
	global_load_dwordx4 v[168:171], v[132:133], off
	v_add_u32_e32 v0, 0x10400, v2
	v_lshl_add_u64 v[132:133], v[0:1], 1, s[16:17]
	global_load_dwordx4 v[160:163], v[132:133], off
	v_add_u32_e32 v0, 0x10480, v2
	v_lshl_add_u64 v[132:133], v[0:1], 1, s[16:17]
	global_load_dwordx4 v[152:155], v[132:133], off
	v_add_u32_e32 v0, 0x18400, v2
	v_lshl_add_u64 v[132:133], v[0:1], 1, s[16:17]
	global_load_dwordx4 v[144:147], v[132:133], off
	v_add_u32_e32 v0, 0x18480, v2
	v_lshl_add_u64 v[132:133], v[0:1], 1, s[16:17]
	global_load_dwordx4 v[136:139], v[132:133], off
	s_and_b64 vcc, exec, s[4:5]
	s_cbranch_vccnz .Lp5_cp_A
	v_mov_b32_e32 v3, v1
	v_lshl_add_u64 v[132:133], v[2:3], 1, s[16:17]
	global_load_dwordx4 v[188:191], v[132:133], off nt
	v_or_b32_e32 v0, 0x80, v2
	v_lshl_add_u64 v[132:133], v[0:1], 1, s[16:17]
	global_load_dwordx4 v[180:183], v[132:133], off nt
	v_add_u32_e32 v0, 0x8000, v2
	v_lshl_add_u64 v[132:133], v[0:1], 1, s[16:17]
	global_load_dwordx4 v[172:175], v[132:133], off nt
	v_add_u32_e32 v0, 0x8080, v2
	v_lshl_add_u64 v[132:133], v[0:1], 1, s[16:17]
	global_load_dwordx4 v[164:167], v[132:133], off nt
	v_add_u32_e32 v0, 0x10000, v2
	v_lshl_add_u64 v[132:133], v[0:1], 1, s[16:17]
	global_load_dwordx4 v[156:159], v[132:133], off nt
	v_add_u32_e32 v0, 0x10080, v2
	v_lshl_add_u64 v[132:133], v[0:1], 1, s[16:17]
	global_load_dwordx4 v[148:151], v[132:133], off nt
	v_add_u32_e32 v0, 0x18000, v2
	v_lshl_add_u64 v[132:133], v[0:1], 1, s[16:17]
	global_load_dwordx4 v[140:143], v[132:133], off nt
	v_add_u32_e32 v0, 0x18080, v2
	v_lshl_add_u64 v[132:133], v[0:1], 1, s[16:17]
	global_load_dwordx4 v[132:135], v[132:133], off nt
	s_waitcnt vmcnt(0)
	s_branch .Lp5_end_A

;     __device__ __forceinline__ void operator()(Acc& acc, const Unit& u, int wr, int wc, int fr, int fq) const {
;     ...
;         for (int ai = 0; ai < 2; ++ai) {
;             u32x4 gw_[4][2], hw_[4][2];
; #pragma unroll
;             for (int m = 0; m < 4; ++m)
; #pragma unroll
;                 for (int bj = 0; bj < 2; ++bj) { const unsigned o = (unsigned)((rowt + ai * 128 + m * 16) * 2048 + c0 + bj * 128);
;                     gw_[m][bj] = *(const u32x4*)(GATES + (o + 1024)); if (u.sel == 0) hw_[m][bj] = *(const u32x4*)(GATES + o); else hw_[m][bj] = gw_[m][bj]; }
.LBB0_940:
	s_waitcnt vmcnt(0)
	v_add_u32_e32 v0, 0x40400, v2
	v_lshl_add_u64 v[132:133], v[0:1], 1, s[16:17]
	global_load_dwordx4 v[192:195], v[132:133], off
	v_add_u32_e32 v0, 0x40480, v2
	v_lshl_add_u64 v[132:133], v[0:1], 1, s[16:17]
	global_load_dwordx4 v[184:187], v[132:133], off
	v_add_u32_e32 v0, 0x48400, v2
	v_lshl_add_u64 v[132:133], v[0:1], 1, s[16:17]
	global_load_dwordx4 v[176:179], v[132:133], off
	v_add_u32_e32 v0, 0x48480, v2
	v_lshl_add_u64 v[132:133], v[0:1], 1, s[16:17]
	global_load_dwordx4 v[168:171], v[132:133], off
	v_add_u32_e32 v0, 0x50400, v2
	v_lshl_add_u64 v[132:133], v[0:1], 1, s[16:17]
	global_load_dwordx4 v[160:163], v[132:133], off
	v_add_u32_e32 v0, 0x50480, v2
	v_lshl_add_u64 v[132:133], v[0:1], 1, s[16:17]
	global_load_dwordx4 v[152:155], v[132:133], off
	v_add_u32_e32 v0, 0x58400, v2
	v_lshl_add_u64 v[132:133], v[0:1], 1, s[16:17]
	global_load_dwordx4 v[144:147], v[132:133], off
	v_add_u32_e32 v0, 0x58480, v2
	v_lshl_add_u64 v[132:133], v[0:1], 1, s[16:17]
	global_load_dwordx4 v[136:139], v[132:133], off
	s_and_b64 vcc, exec, s[4:5]
	s_cbranch_vccnz .Lp5_cp_B
	v_add_u32_e32 v0, 0x40000, v2
	v_lshl_add_u64 v[132:133], v[0:1], 1, s[16:17]
	global_load_dwordx4 v[188:191], v[132:133], off nt
	v_add_u32_e32 v0, 0x40080, v2
	v_lshl_add_u64 v[132:133], v[0:1], 1, s[16:17]
	global_load_dwordx4 v[180:183], v[132:133], off nt
	v_add_u32_e32 v0, 0x48000, v2
	v_lshl_add_u64 v[132:133], v[0:1], 1, s[16:17]
	global_load_dwordx4 v[172:175], v[132:133], off nt
	v_add_u32_e32 v0, 0x48080, v2
	v_lshl_add_u64 v[132:133], v[0:1], 1, s[16:17]
	global_load_dwordx4 v[164:167], v[132:133], off nt
	v_add_u32_e32 v0, 0x50000, v2
	v_lshl_add_u64 v[132:133], v[0:1], 1, s[16:17]
	global_load_dwordx4 v[156:159], v[132:133], off nt
	v_add_u32_e32 v0, 0x50080, v2
	v_lshl_add_u64 v[132:133], v[0:1], 1, s[16:17]
	global_load_dwordx4 v[148:151], v[132:133], off nt
	v_add_u32_e32 v0, 0x58000, v2
	v_lshl_add_u64 v[132:133], v[0:1], 1, s[16:17]
	global_load_dwordx4 v[140:143], v[132:133], off nt
	v_add_u32_e32 v0, 0x58080, v2
	v_lshl_add_u64 v[2:3], v[0:1], 1, s[16:17]
	global_load_dwordx4 v[132:135], v[2:3], off nt
	s_waitcnt vmcnt(0)
	s_branch .Lp5_end_B
